# setup w_in transpose tile: 16 row loads issued together (one wait) instead of one load per wait
# speedup vs baseline: 1.0584x; 1.0078x over previous
; __device__ __forceinline__ void transpose_tile(const float* __restrict__ W, int N, int Kdim, bf16_t* __restrict__ Wt, int k0, int n0,
;                                unsigned char* smem) {
;     ...
; #pragma unroll 4
;   for (int it = 0; it < 16; ++it) {
;     int kk = (tid >> 6) + 4 * it, nn = tid & 63, n = n0 + nn;
;     T[kk * 65 + nn] = (n < N) ? W[(size_t)(k0 + kk) * N + n] : 0.f;
;   }
.LBB0_1373:
	v_mov_b32_e32 v26, 0
	v_mov_b32_e32 v27, 0
	v_mov_b32_e32 v28, 0
	v_mov_b32_e32 v29, 0
	v_mov_b32_e32 v30, 0
	v_mov_b32_e32 v31, 0
	v_mov_b32_e32 v32, 0
	v_mov_b32_e32 v33, 0
	v_mov_b32_e32 v34, 0
	v_mov_b32_e32 v35, 0
	v_mov_b32_e32 v36, 0
	v_mov_b32_e32 v37, 0
	v_mov_b32_e32 v38, 0
	v_mov_b32_e32 v39, 0
	v_mov_b32_e32 v40, 0
	v_mov_b32_e32 v41, 0
	s_and_saveexec_b64 s[56:57], vcc
	v_mad_i64_i32 v[20:21], s[58:59], v17, s35, v[14:15]
	global_load_dword v26, v[20:21], off
	v_add_u32_e32 v18, 4, v17
	v_mad_i64_i32 v[20:21], s[58:59], v18, s35, v[14:15]
	global_load_dword v27, v[20:21], off
	v_add_u32_e32 v18, 8, v17
	v_mad_i64_i32 v[20:21], s[58:59], v18, s35, v[14:15]
	global_load_dword v28, v[20:21], off
	v_add_u32_e32 v18, 12, v17
	v_mad_i64_i32 v[20:21], s[58:59], v18, s35, v[14:15]
	global_load_dword v29, v[20:21], off
	v_add_u32_e32 v18, 16, v17
	v_mad_i64_i32 v[20:21], s[58:59], v18, s35, v[14:15]
	global_load_dword v30, v[20:21], off
	v_add_u32_e32 v18, 20, v17
	v_mad_i64_i32 v[20:21], s[58:59], v18, s35, v[14:15]
	global_load_dword v31, v[20:21], off
	v_add_u32_e32 v18, 24, v17
	v_mad_i64_i32 v[20:21], s[58:59], v18, s35, v[14:15]
	global_load_dword v32, v[20:21], off
	v_add_u32_e32 v18, 28, v17
	v_mad_i64_i32 v[20:21], s[58:59], v18, s35, v[14:15]
	global_load_dword v33, v[20:21], off
	v_add_u32_e32 v18, 32, v17
	v_mad_i64_i32 v[20:21], s[58:59], v18, s35, v[14:15]
	global_load_dword v34, v[20:21], off
	v_add_u32_e32 v18, 36, v17
	v_mad_i64_i32 v[20:21], s[58:59], v18, s35, v[14:15]
	global_load_dword v35, v[20:21], off
	v_add_u32_e32 v18, 40, v17
	v_mad_i64_i32 v[20:21], s[58:59], v18, s35, v[14:15]
	global_load_dword v36, v[20:21], off
	v_add_u32_e32 v18, 44, v17
	v_mad_i64_i32 v[20:21], s[58:59], v18, s35, v[14:15]
	global_load_dword v37, v[20:21], off
	v_add_u32_e32 v18, 48, v17
	v_mad_i64_i32 v[20:21], s[58:59], v18, s35, v[14:15]
	global_load_dword v38, v[20:21], off
	v_add_u32_e32 v18, 52, v17
	v_mad_i64_i32 v[20:21], s[58:59], v18, s35, v[14:15]
	global_load_dword v39, v[20:21], off
	v_add_u32_e32 v18, 56, v17
	v_mad_i64_i32 v[20:21], s[58:59], v18, s35, v[14:15]
	global_load_dword v40, v[20:21], off
	v_add_u32_e32 v18, 60, v17
	v_mad_i64_i32 v[20:21], s[58:59], v18, s35, v[14:15]
	global_load_dword v41, v[20:21], off
	s_or_b64 exec, exec, s[56:57]
	s_waitcnt vmcnt(0)
	ds_write_b32 v16, v26
	ds_write_b32 v16, v27 offset:1040
	ds_write_b32 v16, v28 offset:2080
	ds_write_b32 v16, v29 offset:3120
	ds_write_b32 v16, v30 offset:4160
	ds_write_b32 v16, v31 offset:5200
	ds_write_b32 v16, v32 offset:6240
	ds_write_b32 v16, v33 offset:7280
	ds_write_b32 v16, v34 offset:8320
	ds_write_b32 v16, v35 offset:9360
	ds_write_b32 v16, v36 offset:10400
	ds_write_b32 v16, v37 offset:11440
	ds_write_b32 v16, v38 offset:12480
	ds_write_b32 v16, v39 offset:13520
	ds_write_b32 v16, v40 offset:14560
	ds_write_b32 v16, v41 offset:15600
